# a+b plus P7 fused-rmsnorm epilogue row-sum loads issued together, using in-budget VGPRs v220-226 (descriptor unchanged)
# speedup vs baseline: 1.0106x; 1.0106x over previous
;     __device__ __forceinline__ void operator()(f32x4 (&acc)[2][2][4][2], const Unit& u, int wr, int wc, int fr, int fq) const {
;     ...
;         const float qnan = __builtin_nanf("");
;         f32x4 gv[2][2];
; #pragma unroll
;         for (int bj = 0; bj < 2; ++bj) { gv[bj][0] = *(const f32x4*)(gfin + col0 + bj * HALF); gv[bj][1] = *(const f32x4*)(gfin + col0 + bj * HALF + 4); }
;         float rs[8];
; #pragma unroll
;         for (int g = 0; g < 8; ++g) { const float ss = __hip_atomic_load(rowss + row0 + (g >> 2) * HALF + (g & 3) * 16, __ATOMIC_RELAXED, __HIP_MEMORY_SCOPE_AGENT); rs[g] = dead ? qnan : 1.0f / sqrtf(ss * (1.0f / 4096.0f) + 1e-6f); }
.LBB0_1250:
	global_load_dwordx4 v[8:11], v[146:147], off offset:16
	global_load_dwordx4 v[12:15], v[146:147], off
	global_load_dwordx4 v[0:3], v[146:147], off offset:528
	global_load_dwordx4 v[4:7], v[146:147], off offset:512
	global_load_dword v81, v[162:163], off sc1
	global_load_dword v220, v[162:163], off offset:64 sc1
	global_load_dword v221, v[162:163], off offset:128 sc1
	global_load_dword v222, v[162:163], off offset:192 sc1
	global_load_dword v223, v[162:163], off offset:512 sc1
	global_load_dword v224, v[162:163], off offset:576 sc1
	global_load_dword v225, v[162:163], off offset:640 sc1
	global_load_dword v226, v[162:163], off offset:704 sc1
	v_mov_b32_e32 v80, 0x7fc00000
	s_and_b64 vcc, exec, s[6:7]
	v_mov_b32_e32 v164, 0x7fc00000
	s_cbranch_vccnz .LBB0_1252
	s_waitcnt vmcnt(0)
	v_fmamk_f32 v81, v81, 0x39800000, v181
	v_mul_f32_e32 v82, 0x4f800000, v81
	v_cmp_gt_f32_e32 vcc, s53, v81
	s_nop 1
	v_cndmask_b32_e32 v81, v81, v82, vcc
	v_sqrt_f32_e32 v82, v81
	s_nop 0
	v_add_u32_e32 v83, -1, v82
	v_fma_f32 v85, -v83, v82, v81
	v_add_u32_e32 v84, 1, v82
	v_cmp_ge_f32_e64 s[4:5], 0, v85
	s_nop 1
	v_cndmask_b32_e64 v83, v82, v83, s[4:5]
	v_fma_f32 v82, -v84, v82, v81
	v_cmp_lt_f32_e64 s[4:5], 0, v82
	s_nop 1
	v_cndmask_b32_e64 v82, v83, v84, s[4:5]
	v_mul_f32_e32 v83, 0x37800000, v82
	v_cndmask_b32_e32 v82, v82, v83, vcc
	v_cmp_class_f32_e32 vcc, v81, v182
	s_nop 1
	v_cndmask_b32_e32 v81, v82, v81, vcc
	v_div_scale_f32 v82, s[4:5], v81, v81, 1.0
	v_rcp_f32_e32 v83, v82
	s_nop 0
	v_fma_f32 v84, -v82, v83, 1.0
	v_fmac_f32_e32 v83, v84, v83
	v_div_scale_f32 v84, vcc, 1.0, v81, 1.0
	v_mul_f32_e32 v85, v84, v83
	v_fma_f32 v86, -v82, v85, v84
	v_fmac_f32_e32 v85, v86, v83
	v_fma_f32 v82, -v82, v85, v84
	v_div_fmas_f32 v82, v82, v83, v85
	v_div_fixup_f32 v164, v82, v81, 1.0
.LBB0_1252:
	s_xor_b64 s[6:7], s[6:7], -1
	v_cndmask_b32_e64 v82, 0, 1, s[6:7]
	v_cmp_ne_u32_e64 s[4:5], 1, v82
	s_andn2_b64 vcc, exec, s[6:7]
	s_cbranch_vccnz .LBB0_1254
	s_waitcnt vmcnt(0)
	v_fmamk_f32 v80, v220, 0x39800000, v181
	v_mul_f32_e32 v81, 0x4f800000, v80
	v_cmp_gt_f32_e32 vcc, s53, v80
	s_nop 1
	v_cndmask_b32_e32 v80, v80, v81, vcc
	v_sqrt_f32_e32 v81, v80
	s_nop 0
	v_add_u32_e32 v82, -1, v81
	v_fma_f32 v84, -v82, v81, v80
	v_add_u32_e32 v83, 1, v81
	v_cmp_ge_f32_e64 s[6:7], 0, v84
	s_nop 1
	v_cndmask_b32_e64 v82, v81, v82, s[6:7]
	v_fma_f32 v81, -v83, v81, v80
	v_cmp_lt_f32_e64 s[6:7], 0, v81
	s_nop 1
	v_cndmask_b32_e64 v81, v82, v83, s[6:7]
	v_mul_f32_e32 v82, 0x37800000, v81
	v_cndmask_b32_e32 v81, v81, v82, vcc
	v_cmp_class_f32_e32 vcc, v80, v182
	s_nop 1
	v_cndmask_b32_e32 v80, v81, v80, vcc
	v_div_scale_f32 v81, s[6:7], v80, v80, 1.0
	v_rcp_f32_e32 v82, v81
	s_nop 0
	v_fma_f32 v83, -v81, v82, 1.0
	v_fmac_f32_e32 v82, v83, v82
	v_div_scale_f32 v83, vcc, 1.0, v80, 1.0
	v_mul_f32_e32 v84, v83, v82
	v_fma_f32 v85, -v81, v84, v83
	v_fmac_f32_e32 v84, v85, v82
	v_fma_f32 v81, -v81, v84, v83
	v_div_fmas_f32 v81, v81, v82, v84
	v_div_fixup_f32 v80, v81, v80, 1.0
.LBB0_1254:
	v_mov_b32_e32 v82, 0x7fc00000
	s_and_b64 vcc, exec, s[4:5]
	v_mov_b32_e32 v166, 0x7fc00000
	s_cbranch_vccnz .LBB0_1256
	s_waitcnt vmcnt(0)
	v_fmamk_f32 v81, v221, 0x39800000, v181
	v_mul_f32_e32 v83, 0x4f800000, v81
	v_cmp_gt_f32_e32 vcc, s53, v81
	s_nop 1
	v_cndmask_b32_e32 v81, v81, v83, vcc
	v_sqrt_f32_e32 v83, v81
	s_nop 0
	v_add_u32_e32 v84, -1, v83
	v_fma_f32 v86, -v84, v83, v81
	v_add_u32_e32 v85, 1, v83
	v_cmp_ge_f32_e64 s[6:7], 0, v86
	s_nop 1
	v_cndmask_b32_e64 v84, v83, v84, s[6:7]
	v_fma_f32 v83, -v85, v83, v81
	v_cmp_lt_f32_e64 s[6:7], 0, v83
	s_nop 1
	v_cndmask_b32_e64 v83, v84, v85, s[6:7]
	v_mul_f32_e32 v84, 0x37800000, v83
	v_cndmask_b32_e32 v83, v83, v84, vcc
	v_cmp_class_f32_e32 vcc, v81, v182
	s_nop 1
	v_cndmask_b32_e32 v81, v83, v81, vcc
	v_div_scale_f32 v83, s[6:7], v81, v81, 1.0
	v_rcp_f32_e32 v84, v83
	s_nop 0
	v_fma_f32 v85, -v83, v84, 1.0
	v_fmac_f32_e32 v84, v85, v84
	v_div_scale_f32 v85, vcc, 1.0, v81, 1.0
	v_mul_f32_e32 v86, v85, v84
	v_fma_f32 v87, -v83, v86, v85
	v_fmac_f32_e32 v86, v87, v84
	v_fma_f32 v83, -v83, v86, v85
	v_div_fmas_f32 v83, v83, v84, v86
	v_div_fixup_f32 v166, v83, v81, 1.0
.LBB0_1256:
	s_and_b64 vcc, exec, s[4:5]
	s_cbranch_vccnz .LBB0_1258
	s_waitcnt vmcnt(0)
	v_fmamk_f32 v81, v222, 0x39800000, v181
	v_mul_f32_e32 v82, 0x4f800000, v81
	v_cmp_gt_f32_e32 vcc, s53, v81
	s_nop 1
	v_cndmask_b32_e32 v81, v81, v82, vcc
	v_sqrt_f32_e32 v82, v81
	s_nop 0
	v_add_u32_e32 v83, -1, v82
	v_fma_f32 v85, -v83, v82, v81
	v_add_u32_e32 v84, 1, v82
	v_cmp_ge_f32_e64 s[6:7], 0, v85
	s_nop 1
	v_cndmask_b32_e64 v83, v82, v83, s[6:7]
	v_fma_f32 v82, -v84, v82, v81
	v_cmp_lt_f32_e64 s[6:7], 0, v82
	s_nop 1
	v_cndmask_b32_e64 v82, v83, v84, s[6:7]
	v_mul_f32_e32 v83, 0x37800000, v82
	v_cndmask_b32_e32 v82, v82, v83, vcc
	v_cmp_class_f32_e32 vcc, v81, v182
	s_nop 1
	v_cndmask_b32_e32 v81, v82, v81, vcc
	v_div_scale_f32 v82, s[6:7], v81, v81, 1.0
	v_rcp_f32_e32 v83, v82
	s_nop 0
	v_fma_f32 v84, -v82, v83, 1.0
	v_fmac_f32_e32 v83, v84, v83
	v_div_scale_f32 v84, vcc, 1.0, v81, 1.0
	v_mul_f32_e32 v85, v84, v83
	v_fma_f32 v86, -v82, v85, v84
	v_fmac_f32_e32 v85, v86, v83
	v_fma_f32 v82, -v82, v85, v84
	v_div_fmas_f32 v82, v82, v83, v85
	v_div_fixup_f32 v82, v82, v81, 1.0
;     __device__ __forceinline__ void operator()(f32x4 (&acc)[2][2][4][2], const Unit& u, int wr, int wc, int fr, int fq) const {
;     ...
;         const float qnan = __builtin_nanf("");
;         f32x4 gv[2][2];
; #pragma unroll
;         for (int bj = 0; bj < 2; ++bj) { gv[bj][0] = *(const f32x4*)(gfin + col0 + bj * HALF); gv[bj][1] = *(const f32x4*)(gfin + col0 + bj * HALF + 4); }
;         float rs[8];
; #pragma unroll
;         for (int g = 0; g < 8; ++g) { const float ss = __hip_atomic_load(rowss + row0 + (g >> 2) * HALF + (g & 3) * 16, __ATOMIC_RELAXED, __HIP_MEMORY_SCOPE_AGENT); rs[g] = dead ? qnan : 1.0f / sqrtf(ss * (1.0f / 4096.0f) + 1e-6f); }
.LBB0_1258:
	v_mov_b32_e32 v84, 0x7fc00000
	s_and_b64 vcc, exec, s[4:5]
	v_mov_b32_e32 v168, 0x7fc00000
	s_cbranch_vccnz .LBB0_1260
	s_waitcnt vmcnt(0)
	v_fmamk_f32 v81, v223, 0x39800000, v181
	v_mul_f32_e32 v83, 0x4f800000, v81
	v_cmp_gt_f32_e32 vcc, s53, v81
	s_nop 1
	v_cndmask_b32_e32 v81, v81, v83, vcc
	v_sqrt_f32_e32 v83, v81
	s_nop 0
	v_add_u32_e32 v85, -1, v83
	v_fma_f32 v87, -v85, v83, v81
	v_add_u32_e32 v86, 1, v83
	v_cmp_ge_f32_e64 s[6:7], 0, v87
	s_nop 1
	v_cndmask_b32_e64 v85, v83, v85, s[6:7]
	v_fma_f32 v83, -v86, v83, v81
	v_cmp_lt_f32_e64 s[6:7], 0, v83
	s_nop 1
	v_cndmask_b32_e64 v83, v85, v86, s[6:7]
	v_mul_f32_e32 v85, 0x37800000, v83
	v_cndmask_b32_e32 v83, v83, v85, vcc
	v_cmp_class_f32_e32 vcc, v81, v182
	s_nop 1
	v_cndmask_b32_e32 v81, v83, v81, vcc
	v_div_scale_f32 v83, s[6:7], v81, v81, 1.0
	v_rcp_f32_e32 v85, v83
	s_nop 0
	v_fma_f32 v86, -v83, v85, 1.0
	v_fmac_f32_e32 v85, v86, v85
	v_div_scale_f32 v86, vcc, 1.0, v81, 1.0
	v_mul_f32_e32 v87, v86, v85
	v_fma_f32 v165, -v83, v87, v86
	v_fmac_f32_e32 v87, v165, v85
	v_fma_f32 v83, -v83, v87, v86
	v_div_fmas_f32 v83, v83, v85, v87
	v_div_fixup_f32 v168, v83, v81, 1.0
.LBB0_1260:
	s_and_b64 vcc, exec, s[4:5]
	s_cbranch_vccnz .LBB0_1262
	s_waitcnt vmcnt(0)
	v_fmamk_f32 v81, v224, 0x39800000, v181
	v_mul_f32_e32 v83, 0x4f800000, v81
	v_cmp_gt_f32_e32 vcc, s53, v81
	s_nop 1
	v_cndmask_b32_e32 v81, v81, v83, vcc
	v_sqrt_f32_e32 v83, v81
	s_nop 0
	v_add_u32_e32 v84, -1, v83
	v_fma_f32 v86, -v84, v83, v81
	v_add_u32_e32 v85, 1, v83
	v_cmp_ge_f32_e64 s[6:7], 0, v86
	s_nop 1
	v_cndmask_b32_e64 v84, v83, v84, s[6:7]
	v_fma_f32 v83, -v85, v83, v81
	v_cmp_lt_f32_e64 s[6:7], 0, v83
	s_nop 1
	v_cndmask_b32_e64 v83, v84, v85, s[6:7]
	v_mul_f32_e32 v84, 0x37800000, v83
	v_cndmask_b32_e32 v83, v83, v84, vcc
	v_cmp_class_f32_e32 vcc, v81, v182
	s_nop 1
	v_cndmask_b32_e32 v81, v83, v81, vcc
	v_div_scale_f32 v83, s[6:7], v81, v81, 1.0
	v_rcp_f32_e32 v84, v83
	s_nop 0
	v_fma_f32 v85, -v83, v84, 1.0
	v_fmac_f32_e32 v84, v85, v84
	v_div_scale_f32 v85, vcc, 1.0, v81, 1.0
	v_mul_f32_e32 v86, v85, v84
	v_fma_f32 v87, -v83, v86, v85
	v_fmac_f32_e32 v86, v87, v84
	v_fma_f32 v83, -v83, v86, v85
	v_div_fmas_f32 v83, v83, v84, v86
	v_div_fixup_f32 v84, v83, v81, 1.0
.LBB0_1262:
	v_mov_b32_e32 v86, 0x7fc00000
	s_and_b64 vcc, exec, s[4:5]
	v_mov_b32_e32 v170, 0x7fc00000
	s_cbranch_vccnz .LBB0_1264
	s_waitcnt vmcnt(0)
	v_fmamk_f32 v81, v225, 0x39800000, v181
	v_mul_f32_e32 v83, 0x4f800000, v81
	v_cmp_gt_f32_e32 vcc, s53, v81
	s_nop 1
	v_cndmask_b32_e32 v81, v81, v83, vcc
	v_sqrt_f32_e32 v83, v81
	s_nop 0
	v_add_u32_e32 v85, -1, v83
	v_fma_f32 v165, -v85, v83, v81
	v_add_u32_e32 v87, 1, v83
	v_cmp_ge_f32_e64 s[6:7], 0, v165
	s_nop 1
	v_cndmask_b32_e64 v85, v83, v85, s[6:7]
	v_fma_f32 v83, -v87, v83, v81
	v_cmp_lt_f32_e64 s[6:7], 0, v83
	s_nop 1
	v_cndmask_b32_e64 v83, v85, v87, s[6:7]
	v_mul_f32_e32 v85, 0x37800000, v83
	v_cndmask_b32_e32 v83, v83, v85, vcc
	v_cmp_class_f32_e32 vcc, v81, v182
	s_nop 1
	v_cndmask_b32_e32 v81, v83, v81, vcc
	v_div_scale_f32 v83, s[6:7], v81, v81, 1.0
	v_rcp_f32_e32 v85, v83
	s_nop 0
	v_fma_f32 v87, -v83, v85, 1.0
	v_fmac_f32_e32 v85, v87, v85
	v_div_scale_f32 v87, vcc, 1.0, v81, 1.0
	v_mul_f32_e32 v165, v87, v85
	v_fma_f32 v170, -v83, v165, v87
	v_fmac_f32_e32 v165, v170, v85
	v_fma_f32 v83, -v83, v165, v87
	v_div_fmas_f32 v83, v83, v85, v165
	v_div_fixup_f32 v170, v83, v81, 1.0
.LBB0_1264:
	s_and_b64 vcc, exec, s[4:5]
	s_cbranch_vccnz .LBB0_1266
	s_waitcnt vmcnt(0)
	v_fmamk_f32 v81, v226, 0x39800000, v181
	v_mul_f32_e32 v83, 0x4f800000, v81
	v_cmp_gt_f32_e32 vcc, s53, v81
	s_nop 1
	v_cndmask_b32_e32 v81, v81, v83, vcc
	v_sqrt_f32_e32 v83, v81
	s_nop 0
	v_add_u32_e32 v85, -1, v83
	v_fma_f32 v87, -v85, v83, v81
	v_add_u32_e32 v86, 1, v83
	v_cmp_ge_f32_e64 s[4:5], 0, v87
	s_nop 1
	v_cndmask_b32_e64 v85, v83, v85, s[4:5]
	v_fma_f32 v83, -v86, v83, v81
	v_cmp_lt_f32_e64 s[4:5], 0, v83
	s_nop 1
	v_cndmask_b32_e64 v83, v85, v86, s[4:5]
	v_mul_f32_e32 v85, 0x37800000, v83
	v_cndmask_b32_e32 v83, v83, v85, vcc
	v_cmp_class_f32_e32 vcc, v81, v182
	s_nop 1
	v_cndmask_b32_e32 v81, v83, v81, vcc
	v_div_scale_f32 v83, s[4:5], v81, v81, 1.0
	v_rcp_f32_e32 v85, v83
	s_nop 0
	v_fma_f32 v86, -v83, v85, 1.0
	v_fmac_f32_e32 v85, v86, v85
	v_div_scale_f32 v86, vcc, 1.0, v81, 1.0
	v_mul_f32_e32 v87, v86, v85
	v_fma_f32 v162, -v83, v87, v86
	v_fmac_f32_e32 v87, v162, v85
	v_fma_f32 v83, -v83, v87, v86
	v_div_fmas_f32 v83, v83, v85, v87
	v_div_fixup_f32 v86, v83, v81, 1.0
